# rwkv_seq v3 on both paths: single barrier per chunk, y store + LDS-DMA for chunk c+2 issued right after the barrier; L=2048 path also converted
# speedup vs baseline: 1.0006x; 1.0006x over previous
; #define LAS __attribute__((address_space(3)))
; __device__ __forceinline__ int otid() { int t = threadIdx.x; asm volatile("" : "+v"(t)); return t; }
; __device__ __forceinline__ void rwkv_seq(LAS unsigned char* lds, const MixBufs& B, const bf16_t* rq, int L, int seq, int h, int d) {
;     const int tid = otid(), w = tid >> 6, lane = tid & 63, r = lane & 15, q = lane >> 4;
;     const int tm = w >> 1, tn0 = (w & 1) * 2;
;     const int base = seq * L, nch = L / 64;
;     __syncthreads();
;     for (int i = tid; i < 64 * RL / 2; i += 512) ((LAS unsigned*)lds)[i] = 0u;
;     bf16_t* yout = B.rw_y + (size_t)d * TG * 256;
;     const size_t custride = (size_t)8 * 3 * 4096;
;     const bf16_t* g = rq + (size_t)(((seq * nch) * 4 + h) * 2 + d) * 3 * 4096;
;     const int aoff = (tm * 16 + r) * 64 + q * 8;
;     bf16x8 qa0 = *(const bf16x8*)(g + aoff), qa1 = *(const bf16x8*)(g + aoff + 32);
;     bf16x8 pa0 = *(const bf16x8*)(g + 4096 + aoff), pa1 = *(const bf16x8*)(g + 4096 + aoff + 32);
;     u32x2 hl0 = *(const u32x2*)(g + 8192 + (tn0 * 16 + r) * 64 + tm * 16 + q * 4), hl1 = *(const u32x2*)(g + 8192 + ((tn0 + 1) * 16 + r) * 64 + tm * 16 + q * 4);
;     for (int c = 0; c < nch; ++c) {
;         const bf16_t* gn = g + (c + 1 < nch ? custride : 0);
;         const bf16x8 nqa0 = *(const bf16x8*)(gn + aoff), nqa1 = *(const bf16x8*)(gn + aoff + 32);
;         const bf16x8 npa0 = *(const bf16x8*)(gn + 4096 + aoff), npa1 = *(const bf16x8*)(gn + 4096 + aoff + 32);
;         const u32x2 nhl0 = *(const u32x2*)(gn + 8192 + (tn0 * 16 + r) * 64 + tm * 16 + q * 4), nhl1 = *(const u32x2*)(gn + 8192 + ((tn0 + 1) * 16 + r) * 64 + tm * 16 + q * 4);
;         u32x2 yl[2];
;         const int ti_ = tm * 16 + r;
;         bf16_t* yrow = yout + (size_t)(d == 0 ? base + c * 64 + ti_ : base + L - 1 - (c * 64 + ti_)) * 256 + h * 64 + q * 4;
; #pragma unroll
;         for (int tt = 0; tt < 2; ++tt) yl[tt] = *(const u32x2*)(yrow + (tn0 + tt) * 16);
;         lds_barrier();
;         const LAS bf16_t* cur = (const LAS bf16_t*)(lds + (c & 1) * 9216);
;         LAS bf16_t* nxt = (LAS bf16_t*)(lds + ((c + 1) & 1) * 9216);
; #pragma unroll
;         for (int tt = 0; tt < 2; ++tt) {
;             const int tn = tn0 + tt;
;             const bf16x8 b0 = *(const LAS bf16x8*)(cur + (tn * 16 + r) * RL + q * 8), b1 = *(const LAS bf16x8*)(cur + (tn * 16 + r) * RL + 32 + q * 8);
.LBB0_1353:
	s_or_b64 exec, exec, s[0:1]
	s_ashr_i32 s0, s75, 3
	v_readlane_b32 s1, v247, 42
	s_bfe_u32 s44, s75, 0x20001
	s_lshl_b32 s5, s0, s1
	v_readlane_b32 s1, v247, 15
	s_lshl_b32 s45, s0, s1
	s_lshl_b32 s46, s44, 1
	s_and_b32 s42, s75, 1
	s_or_b32 s0, s46, s45
	s_or_b32 s0, s0, s42
	s_mul_hi_i32 s1, s0, 0x6000
	s_mulk_i32 s0, 0x6000
	v_readlane_b32 s4, v249, 5
	s_nop 0
	s_add_u32 s0, s4, s0
	v_readlane_b32 s4, v249, 6
	s_nop 0
	s_addc_u32 s1, s4, s1
	s_lshl_b32 s6, s42, 24
	v_readlane_b32 s4, v249, 13
	s_nop 0
	s_add_u32 s6, s4, s6
	v_readlane_b32 s4, v249, 14
	s_nop 0
	s_addc_u32 s7, s4, 0
	s_lshl_b32 s4, s44, 7
	s_add_u32 s6, s6, s4
	s_addc_u32 s7, s7, 0
	s_add_i32 s4, s5, s36
	s_sub_i32 s4, s4, 64
	s_movk_i32 s50, 0x8000
	s_cmp_eq_u32 s42, 0
	s_cselect_b32 s4, s5, s4
	s_cselect_b32 s48, 0x8000, s50
	s_cselect_b32 s49, 0, -1
	s_cselect_b64 s[52:53], -1, 0
	s_lshl_b32 s4, s4, 9
	s_add_u32 s6, s6, s4
	s_addc_u32 s7, s7, 0
	s_mov_b32 s46, s6
	s_mov_b32 s47, s7
	s_mov_b32 s43, 0
	s_mov_b32 s16, s64
	s_waitcnt vmcnt(0)
	v_mov_b32_e32 v0, v203
	v_and_b32_e32 v8, 63, v0
	v_lshrrev_b32_e32 v9, 6, v0
	v_lshrrev_b32_e32 v10, 3, v8
	v_and_b32_e32 v11, 7, v8
	v_xor_b32_e32 v11, v11, v10
	v_lshlrev_b32_e32 v11, 4, v11
	v_lshl_or_b32 v12, v10, 7, v11
	v_mul_u32_u24_e32 v13, 0xc00, v9
	v_add_u32_e32 v2, v13, v12
	v_readfirstlane_b32 s4, v9
	v_lshl_or_b32 v14, v9, 3, v10
	v_sub_u32_e32 v15, 63, v14
	v_cndmask_b32_e64 v15, v15, v14, s[52:53]
	v_lshl_or_b32 v3, v15, 9, v11
	v_lshlrev_b32_e32 v16, 4, v8
	v_lshl_or_b32 v16, v9, 10, v16
	v_add_u32_e32 v4, 0x18c00, v16
	v_and_b32_e32 v17, 15, v0
	v_bfe_u32 v18, v0, 4, 2
	v_lshrrev_b32_e32 v19, 7, v0
	v_lshrrev_b32_e32 v20, 5, v0
	v_and_b32_e32 v20, 2, v20
	v_lshl_or_b32 v21, v19, 4, v17
	v_and_b32_e32 v22, 7, v17
	v_lshl_or_b32 v23, v20, 4, v17
	v_mul_u32_u24_e32 v24, 0x90, v23
	v_lshlrev_b32_e32 v25, 4, v18
	v_add_u32_e32 v6, v24, v25
	v_lshlrev_b32_e32 v26, 5, v19
	v_lshl_or_b32 v26, v18, 3, v26
	v_add_u32_e32 v7, v24, v26
	v_xor_b32_e32 v27, v18, v22
	v_lshlrev_b32_e32 v27, 4, v27
	v_lshl_or_b32 v27, v21, 7, v27
	v_add_u32_e32 v45, 0x6c00, v27
	v_xor_b32_e32 v46, 64, v45
	v_lshrrev_b32_e32 v28, 1, v18
	v_lshl_or_b32 v28, v19, 1, v28
	v_xor_b32_e32 v28, v28, v22
	v_lshlrev_b32_e32 v28, 4, v28
	v_and_b32_e32 v29, 1, v18
	v_lshl_or_b32 v28, v29, 3, v28
	v_lshl_or_b32 v28, v23, 7, v28
	v_add_u32_e32 v47, 0xac00, v28
	v_lshrrev_b32_e32 v30, 1, v18
	v_lshl_or_b32 v30, v20, 1, v30
	v_xor_b32_e32 v30, v30, v22
	v_lshlrev_b32_e32 v30, 4, v30
	v_lshl_or_b32 v30, v29, 3, v30
	v_lshl_or_b32 v30, v21, 7, v30
	v_add_u32_e32 v5, 0x18c00, v30
	v_xor_b32_e32 v44, 32, v5
	s_mul_i32 s44, s4, 0xc00
	s_add_i32 s44, s44, 0x6c00
	s_lshl_b32 s45, s4, 10
	s_add_i32 s45, s45, 0x18c00
	s_add_i32 m0, s44, 0
	s_nop 0
	global_load_lds_dwordx4 v2, s[0:1]
	global_load_lds_dwordx4 v2, s[0:1] offset:1024
	global_load_lds_dwordx4 v2, s[0:1] offset:2048
	s_add_i32 m0, s45, 0
	s_nop 0
	global_load_lds_dwordx4 v3, s[46:47]
	s_add_i32 s43, s43, 1
	s_cmp_lt_u32 s43, s64
	s_cselect_b32 s51, 0x30000, 0
	s_cselect_b32 s52, s48, 0
	s_cselect_b32 s53, s49, 0
	s_add_u32 s0, s0, s51
	s_addc_u32 s1, s1, 0
	s_add_u32 s46, s46, s52
	s_addc_u32 s47, s47, s53
	s_add_i32 m0, s44, 24576
	s_nop 0
	global_load_lds_dwordx4 v2, s[0:1]
	global_load_lds_dwordx4 v2, s[0:1] offset:1024
	global_load_lds_dwordx4 v2, s[0:1] offset:2048
	s_add_i32 m0, s45, 8192
	s_nop 0
	global_load_lds_dwordx4 v3, s[46:47]
	s_add_i32 s43, s43, 1
	s_cmp_lt_u32 s43, s64
	s_cselect_b32 s51, 0x30000, 0
	s_cselect_b32 s52, s48, 0
	s_cselect_b32 s53, s49, 0
	s_add_u32 s0, s0, s51
	s_addc_u32 s1, s1, 0
	s_add_u32 s46, s46, s52
	s_addc_u32 s47, s47, s53
	s_waitcnt vmcnt(0)
.Lrws3_gen_loop:
	s_waitcnt vmcnt(5)
	s_waitcnt lgkmcnt(0)
	s_barrier
	ds_read_b128 v[72:75], v4 offset:16384
	ds_read_b128 v[8:11], v6 offset:0
	ds_read_b128 v[48:51], v45 offset:0
	ds_read_b128 v[56:59], v45 offset:8192
	ds_read_b128 v[12:15], v6 offset:64
	ds_read_b128 v[60:63], v46 offset:8192
	ds_read_b128 v[52:55], v46 offset:0
	ds_read_b128 v[16:19], v6 offset:2304
	ds_read_b128 v[20:23], v6 offset:2368
	ds_read_b64 v[64:65], v47 offset:0
	ds_read_b64 v[66:67], v47 offset:2048
	ds_read_b64 v[68:69], v5 offset:0
	ds_read_b64 v[70:71], v44 offset:0
	s_movk_i32 s42, 0
	s_waitcnt lgkmcnt(12)
	s_cmp_eq_u32 s16, s64
	s_cbranch_scc1 .Lrws3_gen_skipst0
	global_store_dwordx4 v3, v[72:75], s[6:7]
	s_add_u32 s6, s6, s48
	s_addc_u32 s7, s7, s49
; #define LAS __attribute__((address_space(3)))
; __device__ __forceinline__ void rwkv_seq(LAS unsigned char* lds, const MixBufs& B, const bf16_t* rq, int L, int seq, int h, int d) {
;     ...
;     for (int c = 0; c < nch; ++c) {
;         const bf16_t* gn = g + (c + 1 < nch ? custride : 0);
;         const bf16x8 nqa0 = *(const bf16x8*)(gn + aoff), nqa1 = *(const bf16x8*)(gn + aoff + 32);
;         const bf16x8 npa0 = *(const bf16x8*)(gn + 4096 + aoff), npa1 = *(const bf16x8*)(gn + 4096 + aoff + 32);
;         const u32x2 nhl0 = *(const u32x2*)(gn + 8192 + (tn0 * 16 + r) * 64 + tm * 16 + q * 4), nhl1 = *(const u32x2*)(gn + 8192 + ((tn0 + 1) * 16 + r) * 64 + tm * 16 + q * 4);
;         u32x2 yl[2];
;         const int ti_ = tm * 16 + r;
;         bf16_t* yrow = yout + (size_t)(d == 0 ? base + c * 64 + ti_ : base + L - 1 - (c * 64 + ti_)) * 256 + h * 64 + q * 4;
; #pragma unroll
;         for (int tt = 0; tt < 2; ++tt) yl[tt] = *(const u32x2*)(yrow + (tn0 + tt) * 16);
;         lds_barrier();
;         const LAS bf16_t* cur = (const LAS bf16_t*)(lds + (c & 1) * 9216);
;         LAS bf16_t* nxt = (LAS bf16_t*)(lds + ((c + 1) & 1) * 9216);
; #pragma unroll
;         for (int tt = 0; tt < 2; ++tt) {
;             const int tn = tn0 + tt;
;             const bf16x8 b0 = *(const LAS bf16x8*)(cur + (tn * 16 + r) * RL + q * 8), b1 = *(const LAS bf16x8*)(cur + (tn * 16 + r) * RL + 32 + q * 8);
;             f32x4 y = (f32x4){0.f, 0.f, 0.f, 0.f}, hn = (f32x4){0.f, 0.f, 0.f, 0.f};
;             y = __builtin_amdgcn_mfma_f32_16x16x32_bf16(b0, qa0, y, 0, 0, 0); y = __builtin_amdgcn_mfma_f32_16x16x32_bf16(b1, qa1, y, 0, 0, 0);
;             hn = __builtin_amdgcn_mfma_f32_16x16x32_bf16(pa0, b0, hn, 0, 0, 0); hn = __builtin_amdgcn_mfma_f32_16x16x32_bf16(pa1, b1, hn, 0, 0, 0);
;             const u32x2 hl = tt == 0 ? hl0 : hl1;
;             hn[0] += __uint_as_float(hl.x << 16); hn[1] += __uint_as_float(hl.x & 0xffff0000u); hn[2] += __uint_as_float(hl.y << 16); hn[3] += __uint_as_float(hl.y & 0xffff0000u);
;             u32x2 o; o.x = pk2(hn[0], hn[1]); o.y = pk2(hn[2], hn[3]);
;             *(LAS u32x2*)(nxt + (tn * 16 + r) * RL + tm * 16 + q * 4) = o;
;             { const u32x2 yo = yl[tt];
;               y[0] += __uint_as_float(yo.x << 16); y[1] += __uint_as_float(yo.x & 0xffff0000u); y[2] += __uint_as_float(yo.y << 16); y[3] += __uint_as_float(yo.y & 0xffff0000u);
.Lrws3_gen_skipst0:
	s_add_i32 m0, s44, 49152
	s_nop 0
	global_load_lds_dwordx4 v2, s[0:1]
	global_load_lds_dwordx4 v2, s[0:1] offset:1024
	global_load_lds_dwordx4 v2, s[0:1] offset:2048
	s_add_i32 m0, s45, 16384
	s_nop 0
	global_load_lds_dwordx4 v3, s[46:47]
	s_add_i32 s43, s43, 1
	s_cmp_lt_u32 s43, s64
	s_cselect_b32 s51, 0x30000, 0
	s_cselect_b32 s52, s48, 0
	s_cselect_b32 s53, s49, 0
	s_add_u32 s0, s0, s51
	s_addc_u32 s1, s1, 0
	s_add_u32 s46, s46, s52
	s_addc_u32 s47, s47, s53
	s_waitcnt lgkmcnt(9)
	v_mfma_f32_16x16x32_bf16 v[24:27], v[8:11], v[48:51], 0
	v_mfma_f32_16x16x32_bf16 v[28:31], v[56:59], v[8:11], 0
	s_waitcnt lgkmcnt(6)
	v_mfma_f32_16x16x32_bf16 v[28:31], v[60:63], v[12:15], v[28:31]
	v_mfma_f32_16x16x32_bf16 v[24:27], v[12:15], v[52:55], v[24:27]
	s_waitcnt lgkmcnt(5)
	v_mfma_f32_16x16x32_bf16 v[36:39], v[56:59], v[16:19], 0
	v_mfma_f32_16x16x32_bf16 v[32:35], v[16:19], v[48:51], 0
	s_waitcnt lgkmcnt(4)
	v_mfma_f32_16x16x32_bf16 v[36:39], v[60:63], v[20:23], v[36:39]
	v_mfma_f32_16x16x32_bf16 v[32:35], v[20:23], v[52:55], v[32:35]
	s_waitcnt lgkmcnt(0)
	v_lshlrev_b32_e32 v40, 16, v64
	v_and_b32_e32 v41, 0xffff0000, v64
	v_lshlrev_b32_e32 v42, 16, v65
	v_and_b32_e32 v43, 0xffff0000, v65
	v_pk_add_f32 v[28:29], v[28:29], v[40:41]
	v_pk_add_f32 v[30:31], v[30:31], v[42:43]
	v_cvt_pk_bf16_f32 v28, v28, v29
	v_cvt_pk_bf16_f32 v29, v30, v31
	ds_write_b64 v7, v[28:29] offset:9216
	v_lshlrev_b32_e32 v40, 16, v66
	v_and_b32_e32 v41, 0xffff0000, v66
	v_lshlrev_b32_e32 v42, 16, v67
	v_and_b32_e32 v43, 0xffff0000, v67
	v_pk_add_f32 v[36:37], v[36:37], v[40:41]
	v_pk_add_f32 v[38:39], v[38:39], v[42:43]
	v_cvt_pk_bf16_f32 v36, v36, v37
	v_cvt_pk_bf16_f32 v37, v38, v39
	ds_write_b64 v7, v[36:37] offset:11520
	v_lshlrev_b32_e32 v40, 16, v68
	v_and_b32_e32 v41, 0xffff0000, v68
	v_lshlrev_b32_e32 v42, 16, v69
	v_and_b32_e32 v43, 0xffff0000, v69
	v_pk_add_f32 v[24:25], v[24:25], v[40:41]
	v_pk_add_f32 v[26:27], v[26:27], v[42:43]
	v_cvt_pk_bf16_f32 v24, v24, v25
	v_cvt_pk_bf16_f32 v25, v26, v27
	ds_write_b64 v5, v[24:25] offset:0
	v_lshlrev_b32_e32 v40, 16, v70
	v_and_b32_e32 v41, 0xffff0000, v70
	v_lshlrev_b32_e32 v42, 16, v71
	v_and_b32_e32 v43, 0xffff0000, v71
	v_pk_add_f32 v[32:33], v[32:33], v[40:41]
	v_pk_add_f32 v[34:35], v[34:35], v[42:43]
	v_cvt_pk_bf16_f32 v32, v32, v33
	v_cvt_pk_bf16_f32 v33, v34, v35
	ds_write_b64 v44, v[32:33] offset:0
	s_add_i32 s16, s16, -1
	s_cmp_eq_u32 s16, 0
	s_cbranch_scc1 .Lrws3_gen_exit
	s_waitcnt vmcnt(5)
	s_waitcnt lgkmcnt(0)
	s_barrier
	ds_read_b128 v[72:75], v4 offset:0
	ds_read_b128 v[8:11], v6 offset:9216
	ds_read_b128 v[48:51], v45 offset:24576
	ds_read_b128 v[56:59], v45 offset:32768
	ds_read_b128 v[12:15], v6 offset:9280
	ds_read_b128 v[60:63], v46 offset:32768
	ds_read_b128 v[52:55], v46 offset:24576
	ds_read_b128 v[16:19], v6 offset:11520
	ds_read_b128 v[20:23], v6 offset:11584
	ds_read_b64 v[64:65], v47 offset:24576
	ds_read_b64 v[66:67], v47 offset:26624
	ds_read_b64 v[68:69], v5 offset:8192
	ds_read_b64 v[70:71], v44 offset:8192
	s_movk_i32 s42, 8192
	s_waitcnt lgkmcnt(12)
	s_cmp_eq_u32 s16, s64
	s_cbranch_scc1 .Lrws3_gen_skipst1
	global_store_dwordx4 v3, v[72:75], s[6:7]
	s_add_u32 s6, s6, s48
	s_addc_u32 s7, s7, s49
; #define LAS __attribute__((address_space(3)))
; __device__ __forceinline__ void rwkv_seq(LAS unsigned char* lds, const MixBufs& B, const bf16_t* rq, int L, int seq, int h, int d) {
;     ...
;     for (int c = 0; c < nch; ++c) {
;         const bf16_t* gn = g + (c + 1 < nch ? custride : 0);
;         const bf16x8 nqa0 = *(const bf16x8*)(gn + aoff), nqa1 = *(const bf16x8*)(gn + aoff + 32);
;         const bf16x8 npa0 = *(const bf16x8*)(gn + 4096 + aoff), npa1 = *(const bf16x8*)(gn + 4096 + aoff + 32);
;         const u32x2 nhl0 = *(const u32x2*)(gn + 8192 + (tn0 * 16 + r) * 64 + tm * 16 + q * 4), nhl1 = *(const u32x2*)(gn + 8192 + ((tn0 + 1) * 16 + r) * 64 + tm * 16 + q * 4);
;         u32x2 yl[2];
;         const int ti_ = tm * 16 + r;
;         bf16_t* yrow = yout + (size_t)(d == 0 ? base + c * 64 + ti_ : base + L - 1 - (c * 64 + ti_)) * 256 + h * 64 + q * 4;
; #pragma unroll
;         for (int tt = 0; tt < 2; ++tt) yl[tt] = *(const u32x2*)(yrow + (tn0 + tt) * 16);
;         lds_barrier();
;         const LAS bf16_t* cur = (const LAS bf16_t*)(lds + (c & 1) * 9216);
;         LAS bf16_t* nxt = (LAS bf16_t*)(lds + ((c + 1) & 1) * 9216);
; #pragma unroll
;         for (int tt = 0; tt < 2; ++tt) {
;             const int tn = tn0 + tt;
;             const bf16x8 b0 = *(const LAS bf16x8*)(cur + (tn * 16 + r) * RL + q * 8), b1 = *(const LAS bf16x8*)(cur + (tn * 16 + r) * RL + 32 + q * 8);
;             f32x4 y = (f32x4){0.f, 0.f, 0.f, 0.f}, hn = (f32x4){0.f, 0.f, 0.f, 0.f};
;             y = __builtin_amdgcn_mfma_f32_16x16x32_bf16(b0, qa0, y, 0, 0, 0); y = __builtin_amdgcn_mfma_f32_16x16x32_bf16(b1, qa1, y, 0, 0, 0);
;             hn = __builtin_amdgcn_mfma_f32_16x16x32_bf16(pa0, b0, hn, 0, 0, 0); hn = __builtin_amdgcn_mfma_f32_16x16x32_bf16(pa1, b1, hn, 0, 0, 0);
;             const u32x2 hl = tt == 0 ? hl0 : hl1;
;             hn[0] += __uint_as_float(hl.x << 16); hn[1] += __uint_as_float(hl.x & 0xffff0000u); hn[2] += __uint_as_float(hl.y << 16); hn[3] += __uint_as_float(hl.y & 0xffff0000u);
;             u32x2 o; o.x = pk2(hn[0], hn[1]); o.y = pk2(hn[2], hn[3]);
;             *(LAS u32x2*)(nxt + (tn * 16 + r) * RL + tm * 16 + q * 4) = o;
;             { const u32x2 yo = yl[tt];
;               y[0] += __uint_as_float(yo.x << 16); y[1] += __uint_as_float(yo.x & 0xffff0000u); y[2] += __uint_as_float(yo.y << 16); y[3] += __uint_as_float(yo.y & 0xffff0000u);
.Lrws3_gen_skipst1:
	s_add_i32 m0, s44, 0
	s_nop 0
	global_load_lds_dwordx4 v2, s[0:1]
	global_load_lds_dwordx4 v2, s[0:1] offset:1024
	global_load_lds_dwordx4 v2, s[0:1] offset:2048
	s_add_i32 m0, s45, 0
	s_nop 0
	global_load_lds_dwordx4 v3, s[46:47]
	s_add_i32 s43, s43, 1
	s_cmp_lt_u32 s43, s64
	s_cselect_b32 s51, 0x30000, 0
	s_cselect_b32 s52, s48, 0
	s_cselect_b32 s53, s49, 0
	s_add_u32 s0, s0, s51
	s_addc_u32 s1, s1, 0
	s_add_u32 s46, s46, s52
	s_addc_u32 s47, s47, s53
	s_waitcnt lgkmcnt(9)
	v_mfma_f32_16x16x32_bf16 v[24:27], v[8:11], v[48:51], 0
	v_mfma_f32_16x16x32_bf16 v[28:31], v[56:59], v[8:11], 0
	s_waitcnt lgkmcnt(6)
	v_mfma_f32_16x16x32_bf16 v[28:31], v[60:63], v[12:15], v[28:31]
	v_mfma_f32_16x16x32_bf16 v[24:27], v[12:15], v[52:55], v[24:27]
	s_waitcnt lgkmcnt(5)
	v_mfma_f32_16x16x32_bf16 v[36:39], v[56:59], v[16:19], 0
	v_mfma_f32_16x16x32_bf16 v[32:35], v[16:19], v[48:51], 0
	s_waitcnt lgkmcnt(4)
	v_mfma_f32_16x16x32_bf16 v[36:39], v[60:63], v[20:23], v[36:39]
	v_mfma_f32_16x16x32_bf16 v[32:35], v[20:23], v[52:55], v[32:35]
	s_waitcnt lgkmcnt(0)
	v_lshlrev_b32_e32 v40, 16, v64
	v_and_b32_e32 v41, 0xffff0000, v64
	v_lshlrev_b32_e32 v42, 16, v65
	v_and_b32_e32 v43, 0xffff0000, v65
	v_pk_add_f32 v[28:29], v[28:29], v[40:41]
	v_pk_add_f32 v[30:31], v[30:31], v[42:43]
	v_cvt_pk_bf16_f32 v28, v28, v29
	v_cvt_pk_bf16_f32 v29, v30, v31
	ds_write_b64 v7, v[28:29] offset:18432
	v_lshlrev_b32_e32 v40, 16, v66
	v_and_b32_e32 v41, 0xffff0000, v66
	v_lshlrev_b32_e32 v42, 16, v67
	v_and_b32_e32 v43, 0xffff0000, v67
	v_pk_add_f32 v[36:37], v[36:37], v[40:41]
	v_pk_add_f32 v[38:39], v[38:39], v[42:43]
	v_cvt_pk_bf16_f32 v36, v36, v37
	v_cvt_pk_bf16_f32 v37, v38, v39
	ds_write_b64 v7, v[36:37] offset:20736
	v_lshlrev_b32_e32 v40, 16, v68
	v_and_b32_e32 v41, 0xffff0000, v68
	v_lshlrev_b32_e32 v42, 16, v69
	v_and_b32_e32 v43, 0xffff0000, v69
	v_pk_add_f32 v[24:25], v[24:25], v[40:41]
	v_pk_add_f32 v[26:27], v[26:27], v[42:43]
	v_cvt_pk_bf16_f32 v24, v24, v25
	v_cvt_pk_bf16_f32 v25, v26, v27
	ds_write_b64 v5, v[24:25] offset:8192
	v_lshlrev_b32_e32 v40, 16, v70
	v_and_b32_e32 v41, 0xffff0000, v70
	v_lshlrev_b32_e32 v42, 16, v71
	v_and_b32_e32 v43, 0xffff0000, v71
	v_pk_add_f32 v[32:33], v[32:33], v[40:41]
	v_pk_add_f32 v[34:35], v[34:35], v[42:43]
	v_cvt_pk_bf16_f32 v32, v32, v33
	v_cvt_pk_bf16_f32 v33, v34, v35
	ds_write_b64 v44, v[32:33] offset:8192
	s_add_i32 s16, s16, -1
	s_cmp_eq_u32 s16, 0
	s_cbranch_scc1 .Lrws3_gen_exit
	s_waitcnt vmcnt(5)
	s_waitcnt lgkmcnt(0)
	s_barrier
	ds_read_b128 v[72:75], v4 offset:8192
	ds_read_b128 v[8:11], v6 offset:18432
	ds_read_b128 v[48:51], v45 offset:49152
	ds_read_b128 v[56:59], v45 offset:57344
	ds_read_b128 v[12:15], v6 offset:18496
	ds_read_b128 v[60:63], v46 offset:57344
	ds_read_b128 v[52:55], v46 offset:49152
	ds_read_b128 v[16:19], v6 offset:20736
	ds_read_b128 v[20:23], v6 offset:20800
	ds_read_b64 v[64:65], v47 offset:49152
	ds_read_b64 v[66:67], v47 offset:51200
	ds_read_b64 v[68:69], v5 offset:16384
	ds_read_b64 v[70:71], v44 offset:16384
	s_movk_i32 s42, 16384
	s_waitcnt lgkmcnt(12)
	s_cmp_eq_u32 s16, s64
	s_cbranch_scc1 .Lrws3_gen_skipst2
	global_store_dwordx4 v3, v[72:75], s[6:7]
	s_add_u32 s6, s6, s48
	s_addc_u32 s7, s7, s49
.Lrws3_gen_skipst2:
	s_add_i32 m0, s44, 24576
	s_nop 0
	global_load_lds_dwordx4 v2, s[0:1]
	global_load_lds_dwordx4 v2, s[0:1] offset:1024
	global_load_lds_dwordx4 v2, s[0:1] offset:2048
	s_add_i32 m0, s45, 8192
	s_nop 0
	global_load_lds_dwordx4 v3, s[46:47]
	s_add_i32 s43, s43, 1
	s_cmp_lt_u32 s43, s64
	s_cselect_b32 s51, 0x30000, 0
	s_cselect_b32 s52, s48, 0
	s_cselect_b32 s53, s49, 0
	s_add_u32 s0, s0, s51
	s_addc_u32 s1, s1, 0
	s_add_u32 s46, s46, s52
	s_addc_u32 s47, s47, s53
	s_waitcnt lgkmcnt(9)
	v_mfma_f32_16x16x32_bf16 v[24:27], v[8:11], v[48:51], 0
	v_mfma_f32_16x16x32_bf16 v[28:31], v[56:59], v[8:11], 0
	s_waitcnt lgkmcnt(6)
	v_mfma_f32_16x16x32_bf16 v[28:31], v[60:63], v[12:15], v[28:31]
	v_mfma_f32_16x16x32_bf16 v[24:27], v[12:15], v[52:55], v[24:27]
	s_waitcnt lgkmcnt(5)
	v_mfma_f32_16x16x32_bf16 v[36:39], v[56:59], v[16:19], 0
	v_mfma_f32_16x16x32_bf16 v[32:35], v[16:19], v[48:51], 0
	s_waitcnt lgkmcnt(4)
	v_mfma_f32_16x16x32_bf16 v[36:39], v[60:63], v[20:23], v[36:39]
	v_mfma_f32_16x16x32_bf16 v[32:35], v[20:23], v[52:55], v[32:35]
	s_waitcnt lgkmcnt(0)
	v_lshlrev_b32_e32 v40, 16, v64
	v_and_b32_e32 v41, 0xffff0000, v64
	v_lshlrev_b32_e32 v42, 16, v65
	v_and_b32_e32 v43, 0xffff0000, v65
	v_pk_add_f32 v[28:29], v[28:29], v[40:41]
	v_pk_add_f32 v[30:31], v[30:31], v[42:43]
	v_cvt_pk_bf16_f32 v28, v28, v29
	v_cvt_pk_bf16_f32 v29, v30, v31
	ds_write_b64 v7, v[28:29] offset:0
	v_lshlrev_b32_e32 v40, 16, v66
	v_and_b32_e32 v41, 0xffff0000, v66
	v_lshlrev_b32_e32 v42, 16, v67
	v_and_b32_e32 v43, 0xffff0000, v67
	v_pk_add_f32 v[36:37], v[36:37], v[40:41]
	v_pk_add_f32 v[38:39], v[38:39], v[42:43]
	v_cvt_pk_bf16_f32 v36, v36, v37
	v_cvt_pk_bf16_f32 v37, v38, v39
	ds_write_b64 v7, v[36:37] offset:2304
	v_lshlrev_b32_e32 v40, 16, v68
	v_and_b32_e32 v41, 0xffff0000, v68
	v_lshlrev_b32_e32 v42, 16, v69
	v_and_b32_e32 v43, 0xffff0000, v69
	v_pk_add_f32 v[24:25], v[24:25], v[40:41]
	v_pk_add_f32 v[26:27], v[26:27], v[42:43]
	v_cvt_pk_bf16_f32 v24, v24, v25
	v_cvt_pk_bf16_f32 v25, v26, v27
	ds_write_b64 v5, v[24:25] offset:16384
	v_lshlrev_b32_e32 v40, 16, v70
	v_and_b32_e32 v41, 0xffff0000, v70
	v_lshlrev_b32_e32 v42, 16, v71
	v_and_b32_e32 v43, 0xffff0000, v71
	v_pk_add_f32 v[32:33], v[32:33], v[40:41]
	v_pk_add_f32 v[34:35], v[34:35], v[42:43]
	v_cvt_pk_bf16_f32 v32, v32, v33
	v_cvt_pk_bf16_f32 v33, v34, v35
	ds_write_b64 v44, v[32:33] offset:16384
	s_add_i32 s16, s16, -1
	s_cmp_eq_u32 s16, 0
	s_cbranch_scc1 .Lrws3_gen_exit
	s_branch .Lrws3_gen_loop
.Lrws3_gen_exit:
	s_waitcnt lgkmcnt(0)
	s_barrier
	v_add_u32_e32 v8, s42, v4
	ds_read_b128 v[72:75], v8
	s_waitcnt lgkmcnt(0)
	global_store_dwordx4 v3, v[72:75], s[6:7]
	s_waitcnt vmcnt(0)
	v_readlane_b32 s44, v248, 19
	v_readlane_b32 s45, v248, 20
	v_readlane_b32 s46, v248, 21
	v_readlane_b32 s47, v248, 22
	v_readlane_b32 s48, v248, 23
	v_readlane_b32 s49, v248, 24
	v_readlane_b32 s50, v248, 25
	v_readlane_b32 s51, v248, 26
	v_readlane_b32 s52, v248, 27
	v_readlane_b32 s53, v248, 28
	v_readlane_b32 s54, v248, 29
	v_readlane_b32 s55, v248, 30
	v_readlane_b32 s56, v248, 31
	v_readlane_b32 s57, v248, 32
	v_readlane_b32 s58, v248, 33
	v_readlane_b32 s59, v248, 34
	s_branch .LBB0_1292

; #define LAS __attribute__((address_space(3)))
; __device__ __forceinline__ int otid() { int t = threadIdx.x; asm volatile("" : "+v"(t)); return t; }
; __device__ __forceinline__ void rwkv_seq(LAS unsigned char* lds, const MixBufs& B, const bf16_t* rq, int L, int seq, int h, int d) {
;     const int tid = otid(), w = tid >> 6, lane = tid & 63, r = lane & 15, q = lane >> 4;
;     const int tm = w >> 1, tn0 = (w & 1) * 2;
;     const int base = seq * L, nch = L / 64;
;     __syncthreads();
;     for (int i = tid; i < 64 * RL / 2; i += 512) ((LAS unsigned*)lds)[i] = 0u;
;     bf16_t* yout = B.rw_y + (size_t)d * TG * 256;
;     const size_t custride = (size_t)8 * 3 * 4096;
;     const bf16_t* g = rq + (size_t)(((seq * nch) * 4 + h) * 2 + d) * 3 * 4096;
;     const int aoff = (tm * 16 + r) * 64 + q * 8;
;     bf16x8 qa0 = *(const bf16x8*)(g + aoff), qa1 = *(const bf16x8*)(g + aoff + 32);
;     bf16x8 pa0 = *(const bf16x8*)(g + 4096 + aoff), pa1 = *(const bf16x8*)(g + 4096 + aoff + 32);
;     u32x2 hl0 = *(const u32x2*)(g + 8192 + (tn0 * 16 + r) * 64 + tm * 16 + q * 4), hl1 = *(const u32x2*)(g + 8192 + ((tn0 + 1) * 16 + r) * 64 + tm * 16 + q * 4);
;     for (int c = 0; c < nch; ++c) {
;         const bf16_t* gn = g + (c + 1 < nch ? custride : 0);
;         const bf16x8 nqa0 = *(const bf16x8*)(gn + aoff), nqa1 = *(const bf16x8*)(gn + aoff + 32);
;         const bf16x8 npa0 = *(const bf16x8*)(gn + 4096 + aoff), npa1 = *(const bf16x8*)(gn + 4096 + aoff + 32);
;         const u32x2 nhl0 = *(const u32x2*)(gn + 8192 + (tn0 * 16 + r) * 64 + tm * 16 + q * 4), nhl1 = *(const u32x2*)(gn + 8192 + ((tn0 + 1) * 16 + r) * 64 + tm * 16 + q * 4);
; __global__ void __launch_bounds__(512, 2) fwd_megakernel(Params P) {
;     ...
;                 if (nseg == 1 && G == 256) {
;                     const int b = blockIdx.x;
;                     if (b < 128) rwkv_seq(lds, B, rq, L, b >> 3, (b >> 1) & 3, b & 1);
.LBB0_1382:
	s_or_b64 exec, exec, s[0:1]
	v_writelane_b32 v246, s4, 1
	v_writelane_b32 v246, s16, 2
	v_writelane_b32 v246, s42, 3
	v_writelane_b32 v246, s43, 4
	v_writelane_b32 v246, s44, 5
	v_writelane_b32 v246, s45, 6
	v_writelane_b32 v246, s46, 7
	v_writelane_b32 v246, s47, 8
	v_writelane_b32 v246, s48, 9
	v_writelane_b32 v246, s49, 10
	v_writelane_b32 v246, s50, 11
	v_writelane_b32 v246, s51, 12
	v_writelane_b32 v246, s52, 13
	v_writelane_b32 v246, s53, 14
	v_readlane_b32 s2, v248, 60
	s_nop 3
	s_ashr_i32 s0, s2, 3
	v_readlane_b32 s1, v247, 42
	s_bfe_u32 s44, s2, 0x20001
	s_lshl_b32 s5, s0, s1
	v_readlane_b32 s1, v247, 15
	s_lshl_b32 s45, s0, s1
	s_lshl_b32 s46, s44, 1
	s_and_b32 s42, s2, 1
	s_or_b32 s0, s46, s45
	s_or_b32 s0, s0, s42
	s_mul_hi_i32 s1, s0, 0x6000
	s_mulk_i32 s0, 0x6000
	v_readlane_b32 s4, v249, 5
	s_nop 0
	s_add_u32 s0, s4, s0
	v_readlane_b32 s4, v249, 6
	s_nop 0
	s_addc_u32 s1, s4, s1
	s_lshl_b32 s6, s42, 24
	v_readlane_b32 s4, v249, 13
	s_nop 0
	s_add_u32 s6, s4, s6
	v_readlane_b32 s4, v249, 14
	s_nop 0
	s_addc_u32 s7, s4, 0
	s_lshl_b32 s4, s44, 7
	s_add_u32 s6, s6, s4
	s_addc_u32 s7, s7, 0
	s_add_i32 s4, s5, s36
	s_sub_i32 s4, s4, 64
	s_movk_i32 s50, 0x8000
	s_cmp_eq_u32 s42, 0
	s_cselect_b32 s4, s5, s4
	s_cselect_b32 s48, 0x8000, s50
	s_cselect_b32 s49, 0, -1
	s_cselect_b64 s[52:53], -1, 0
	s_lshl_b32 s4, s4, 9
	s_add_u32 s6, s6, s4
	s_addc_u32 s7, s7, 0
	s_mov_b32 s46, s6
	s_mov_b32 s47, s7
	s_mov_b32 s43, 0
	s_mov_b32 s16, s64
	s_waitcnt vmcnt(0)
	v_mov_b32_e32 v0, v203
	v_and_b32_e32 v8, 63, v0
	v_lshrrev_b32_e32 v9, 6, v0
	v_lshrrev_b32_e32 v10, 3, v8
	v_and_b32_e32 v11, 7, v8
	v_xor_b32_e32 v11, v11, v10
	v_lshlrev_b32_e32 v11, 4, v11
	v_lshl_or_b32 v12, v10, 7, v11
	v_mul_u32_u24_e32 v13, 0xc00, v9
	v_add_u32_e32 v2, v13, v12
	v_readfirstlane_b32 s4, v9
	v_lshl_or_b32 v14, v9, 3, v10
	v_sub_u32_e32 v15, 63, v14
	v_cndmask_b32_e64 v15, v15, v14, s[52:53]
	v_lshl_or_b32 v3, v15, 9, v11
	v_lshlrev_b32_e32 v16, 4, v8
	v_lshl_or_b32 v16, v9, 10, v16
	v_add_u32_e32 v4, 0x18c00, v16
	v_and_b32_e32 v17, 15, v0
	v_bfe_u32 v18, v0, 4, 2
	v_lshrrev_b32_e32 v19, 7, v0
	v_lshrrev_b32_e32 v20, 5, v0
	v_and_b32_e32 v20, 2, v20
	v_lshl_or_b32 v21, v19, 4, v17
	v_and_b32_e32 v22, 7, v17
	v_lshl_or_b32 v23, v20, 4, v17
	v_mul_u32_u24_e32 v24, 0x90, v23
	v_lshlrev_b32_e32 v25, 4, v18
	v_add_u32_e32 v6, v24, v25
	v_lshlrev_b32_e32 v26, 5, v19
	v_lshl_or_b32 v26, v18, 3, v26
	v_add_u32_e32 v7, v24, v26
	v_xor_b32_e32 v27, v18, v22
	v_lshlrev_b32_e32 v27, 4, v27
	v_lshl_or_b32 v27, v21, 7, v27
	v_add_u32_e32 v45, 0x6c00, v27
	v_xor_b32_e32 v46, 64, v45
	v_lshrrev_b32_e32 v28, 1, v18
	v_lshl_or_b32 v28, v19, 1, v28
	v_xor_b32_e32 v28, v28, v22
	v_lshlrev_b32_e32 v28, 4, v28
	v_and_b32_e32 v29, 1, v18
	v_lshl_or_b32 v28, v29, 3, v28
	v_lshl_or_b32 v28, v23, 7, v28
	v_add_u32_e32 v47, 0xac00, v28
	v_lshrrev_b32_e32 v30, 1, v18
	v_lshl_or_b32 v30, v20, 1, v30
	v_xor_b32_e32 v30, v30, v22
	v_lshlrev_b32_e32 v30, 4, v30
	v_lshl_or_b32 v30, v29, 3, v30
	v_lshl_or_b32 v30, v21, 7, v30
	v_add_u32_e32 v5, 0x18c00, v30
	v_xor_b32_e32 v44, 32, v5
	s_mul_i32 s44, s4, 0xc00
	s_add_i32 s44, s44, 0x6c00
	s_lshl_b32 s45, s4, 10
	s_add_i32 s45, s45, 0x18c00
	s_add_i32 m0, s44, 0
	s_nop 0
	global_load_lds_dwordx4 v2, s[0:1]
	global_load_lds_dwordx4 v2, s[0:1] offset:1024
	global_load_lds_dwordx4 v2, s[0:1] offset:2048
	s_add_i32 m0, s45, 0
	s_nop 0
	global_load_lds_dwordx4 v3, s[46:47]
	s_add_i32 s43, s43, 1
	s_cmp_lt_u32 s43, s64
	s_cselect_b32 s51, 0x30000, 0
	s_cselect_b32 s52, s48, 0
	s_cselect_b32 s53, s49, 0
	s_add_u32 s0, s0, s51
	s_addc_u32 s1, s1, 0
	s_add_u32 s46, s46, s52
	s_addc_u32 s47, s47, s53
	s_add_i32 m0, s44, 24576
	s_nop 0
	global_load_lds_dwordx4 v2, s[0:1]
	global_load_lds_dwordx4 v2, s[0:1] offset:1024
	global_load_lds_dwordx4 v2, s[0:1] offset:2048
	s_add_i32 m0, s45, 8192
	s_nop 0
	global_load_lds_dwordx4 v3, s[46:47]
	s_add_i32 s43, s43, 1
	s_cmp_lt_u32 s43, s64
	s_cselect_b32 s51, 0x30000, 0
	s_cselect_b32 s52, s48, 0
	s_cselect_b32 s53, s49, 0
	s_add_u32 s0, s0, s51
	s_addc_u32 s1, s1, 0
	s_add_u32 s46, s46, s52
	s_addc_u32 s47, s47, s53
	s_waitcnt vmcnt(0)

; __device__ __forceinline__ unsigned pk2(float lo, float hi) { f32x2 f = {lo, hi}; bf16x2_t v = __builtin_convertvector(f, bf16x2_t); return __builtin_bit_cast(unsigned, v); }
; __device__ __forceinline__ void rwkv_seq(LAS unsigned char* lds, const MixBufs& B, const bf16_t* rq, int L, int seq, int h, int d) {
;     ...
;             { const u32x2 yo = yl[tt];
;               y[0] += __uint_as_float(yo.x << 16); y[1] += __uint_as_float(yo.x & 0xffff0000u); y[2] += __uint_as_float(yo.y << 16); y[3] += __uint_as_float(yo.y & 0xffff0000u);
;               u32x2 o2; o2.x = pk2(y[0], y[1]); o2.y = pk2(y[2], y[3]); *(u32x2*)(yrow + tn * 16) = o2; }
;         }
;         g = gn; qa0 = nqa0; qa1 = nqa1; pa0 = npa0; pa1 = npa1; hl0 = nhl0; hl1 = nhl1;
;     }
.Lrws3_fast_exit:
	s_waitcnt lgkmcnt(0)
	s_barrier
	v_add_u32_e32 v8, s42, v4
	ds_read_b128 v[72:75], v8
	s_waitcnt lgkmcnt(0)
	global_store_dwordx4 v3, v[72:75], s[6:7]
	s_waitcnt vmcnt(0)
	v_readlane_b32 s4, v246, 1
	v_readlane_b32 s16, v246, 2
	v_readlane_b32 s42, v246, 3
	v_readlane_b32 s43, v246, 4
	v_readlane_b32 s44, v246, 5
	v_readlane_b32 s45, v246, 6
	v_readlane_b32 s46, v246, 7
	v_readlane_b32 s47, v246, 8
	v_readlane_b32 s48, v246, 9
	v_readlane_b32 s49, v246, 10
	v_readlane_b32 s50, v246, 11
	v_readlane_b32 s51, v246, 12
	v_readlane_b32 s52, v246, 13
	v_readlane_b32 s53, v246, 14
	s_nop 4
